# E42: grid barrier - non-leader workgroups poll the top release generation directly instead of waiting for their XCD leader to republish it (one fabric hop less per barrier)
# speedup vs baseline: 1.0092x; 1.0092x over previous
; DI unsigned xb_ld(unsigned* p)              { return __hip_atomic_load(p, __ATOMIC_RELAXED, __HIP_MEMORY_SCOPE_AGENT); }
; DI unsigned xb_add(unsigned* p, unsigned v) { return __hip_atomic_fetch_add(p, v, __ATOMIC_RELAXED, __HIP_MEMORY_SCOPE_AGENT); }
; #define XB_SPIN(cond, bar) do { unsigned _sp = 0; while (cond) { __builtin_amdgcn_s_sleep(1); \
;     if ((++_sp & 255u) == 0u) { if (xb_ld(&(bar)[XB_TMO])) break; if (_sp > XB_SPIN_CAP) { atomicAdd(&(bar)[XB_TMO], 1u); break; } } } } while (0)
; DI void xcd_barrier(const XcdBarrier& b) {
;     ...
;         const unsigned old = xb_add(&bar[XB_XSUB(b.x)], 1u);
;         const unsigned gen = old / nloc;
;         if (old + 1u == (gen + 1u) * nloc) {
;             __builtin_amdgcn_fence(__ATOMIC_RELEASE, "agent");
;             asm volatile("s_waitcnt vmcnt(0)" ::: "memory");
;             const unsigned og = xb_add(&bar[XB_TOP], 1u);
;             const unsigned tg = og / nx;
;             if (og + 1u == (tg + 1u) * nx) xb_add(&bar[XB_TOPGEN], 1u);
;             else XB_SPIN(xb_ld(&bar[XB_TOPGEN]) == tg, bar);
;             __builtin_amdgcn_fence(__ATOMIC_ACQUIRE, "agent");
;             xb_add(&bar[XB_XGEN(b.x)], 1u);
;             asm volatile("s_waitcnt vmcnt(0)" ::: "memory");
;         } else {
;             XB_SPIN(xb_ld(&bar[XB_XGEN(b.x)]) == gen, bar);
.LBB0_58:
	s_lshl_b32 s8, s3, 8
	s_add_u32 s8, s40, s8
	s_addc_u32 s9, s41, 0
	v_mov_b32_e32 v1, 0x1000
	v_mov_b32_e32 v3, 1
	global_atomic_add v3, v1, v3, s[8:9] offset:1024 sc0
	v_cvt_f32_u32_e32 v1, v2
	v_sub_u32_e32 v4, 0, v2
	s_add_u32 s8, s8, 0x2400
	s_addc_u32 s9, s9, 0
	v_rcp_iflag_f32_e32 v1, v1
	s_nop 0
	v_mul_f32_e32 v1, 0x4f7ffffe, v1
	v_cvt_u32_f32_e32 v1, v1
	v_mul_lo_u32 v4, v4, v1
	v_mul_hi_u32 v4, v1, v4
	v_add_u32_e32 v1, v1, v4
	s_waitcnt vmcnt(0)
	v_mul_hi_u32 v1, v3, v1
	v_mul_lo_u32 v4, v1, v2
	v_sub_u32_e32 v4, v3, v4
	v_add_u32_e32 v5, 1, v1
	v_cmp_ge_u32_e32 vcc, v4, v2
	v_add_u32_e32 v3, 1, v3
	s_nop 0
	v_cndmask_b32_e32 v1, v1, v5, vcc
	v_sub_u32_e32 v5, v4, v2
	v_cndmask_b32_e32 v4, v4, v5, vcc
	v_add_u32_e32 v5, 1, v1
	v_cmp_ge_u32_e32 vcc, v4, v2
	s_nop 1
	v_cndmask_b32_e32 v1, v1, v5, vcc
	v_mul_lo_u32 v4, v2, v1
	v_add_u32_e32 v2, v4, v2
	v_cmp_ne_u32_e32 vcc, v3, v2
	s_and_saveexec_b64 s[10:11], vcc
	s_xor_b64 s[10:11], exec, s[10:11]
	s_cbranch_execz .LBB0_72
	s_add_u32 s8, s6, 0x3300
	s_addc_u32 s9, s7, 0
	s_waitcnt lgkmcnt(0)
	v_mov_b32_e32 v0, 0
	global_load_dword v2, v0, s[8:9] sc1
	s_waitcnt vmcnt(0)
	v_cmp_eq_u32_e32 vcc, v2, v1
	s_and_saveexec_b64 s[12:13], vcc
	s_cbranch_execz .LBB0_71
	s_mov_b32 s24, 1
	s_mov_b64 s[14:15], 0
	s_branch .LBB0_62

; DI unsigned xb_ld(unsigned* p)              { return __hip_atomic_load(p, __ATOMIC_RELAXED, __HIP_MEMORY_SCOPE_AGENT); }
; DI unsigned xb_add(unsigned* p, unsigned v) { return __hip_atomic_fetch_add(p, v, __ATOMIC_RELAXED, __HIP_MEMORY_SCOPE_AGENT); }
; #define XB_SPIN(cond, bar) do { unsigned _sp = 0; while (cond) { __builtin_amdgcn_s_sleep(1); \
;     if ((++_sp & 255u) == 0u) { if (xb_ld(&(bar)[XB_TMO])) break; if (_sp > XB_SPIN_CAP) { atomicAdd(&(bar)[XB_TMO], 1u); break; } } } } while (0)
; DI void xcd_barrier(const XcdBarrier& b) {
;     ...
;         const unsigned old = xb_add(&bar[XB_XSUB(b.x)], 1u);
;         const unsigned gen = old / nloc;
;         if (old + 1u == (gen + 1u) * nloc) {
;             __builtin_amdgcn_fence(__ATOMIC_RELEASE, "agent");
;             asm volatile("s_waitcnt vmcnt(0)" ::: "memory");
;             const unsigned og = xb_add(&bar[XB_TOP], 1u);
;             const unsigned tg = og / nx;
;             if (og + 1u == (tg + 1u) * nx) xb_add(&bar[XB_TOPGEN], 1u);
;             else XB_SPIN(xb_ld(&bar[XB_TOPGEN]) == tg, bar);
;             __builtin_amdgcn_fence(__ATOMIC_ACQUIRE, "agent");
;             xb_add(&bar[XB_XGEN(b.x)], 1u);
;             asm volatile("s_waitcnt vmcnt(0)" ::: "memory");
;         } else {
;             XB_SPIN(xb_ld(&bar[XB_XGEN(b.x)]) == gen, bar);
.LBB0_1005:
	v_readlane_b32 s4, v253, 52
	v_readlane_b32 s5, v253, 53
	v_cvt_f32_u32_e32 v1, v2
	v_sub_u32_e32 v4, 0, v2
	v_rcp_iflag_f32_e32 v1, v1
	s_nop 1
	global_atomic_add v3, v173, v237, s[4:5] sc0
	v_mul_f32_e32 v1, 0x4f7ffffe, v1
	v_cvt_u32_f32_e32 v1, v1
	v_mul_lo_u32 v4, v4, v1
	v_mul_hi_u32 v4, v1, v4
	v_add_u32_e32 v1, v1, v4
	s_waitcnt vmcnt(0)
	v_mul_hi_u32 v1, v3, v1
	v_mul_lo_u32 v4, v1, v2
	v_sub_u32_e32 v4, v3, v4
	v_add_u32_e32 v5, 1, v1
	v_cmp_ge_u32_e32 vcc, v4, v2
	v_add_u32_e32 v3, 1, v3
	s_nop 0
	v_cndmask_b32_e32 v1, v1, v5, vcc
	v_sub_u32_e32 v5, v4, v2
	v_cndmask_b32_e32 v4, v4, v5, vcc
	v_add_u32_e32 v5, 1, v1
	v_cmp_ge_u32_e32 vcc, v4, v2
	s_nop 1
	v_cndmask_b32_e32 v1, v1, v5, vcc
	v_mul_lo_u32 v4, v2, v1
	v_add_u32_e32 v2, v4, v2
	v_cmp_ne_u32_e32 vcc, v3, v2
	s_and_saveexec_b64 s[4:5], vcc
	s_xor_b64 s[4:5], exec, s[4:5]
	s_cbranch_execz .LBB0_1019
	s_add_u32 s6, s62, 0x3300
	s_addc_u32 s7, s63, 0
	s_waitcnt lgkmcnt(0)
	s_nop 3
	global_load_dword v0, v173, s[6:7] sc1
	s_waitcnt vmcnt(0)
	v_cmp_eq_u32_e32 vcc, v0, v1
	s_and_saveexec_b64 s[6:7], vcc
	s_cbranch_execz .LBB0_1018
	s_mov_b32 s18, 1
	s_mov_b64 s[8:9], 0
	s_branch .LBB0_1009

; DI unsigned xb_ld(unsigned* p)              { return __hip_atomic_load(p, __ATOMIC_RELAXED, __HIP_MEMORY_SCOPE_AGENT); }
; #define XB_SPIN(cond, bar) do { unsigned _sp = 0; while (cond) { __builtin_amdgcn_s_sleep(1); \
;     if ((++_sp & 255u) == 0u) { if (xb_ld(&(bar)[XB_TMO])) break; if (_sp > XB_SPIN_CAP) { atomicAdd(&(bar)[XB_TMO], 1u); break; } } } } while (0)
; DI void xcd_barrier(const XcdBarrier& b) {
;     ...
;             XB_SPIN(xb_ld(&bar[XB_XGEN(b.x)]) == gen, bar);
.LBB0_1011:
	s_add_u32 s12, s62, 0x3300
	s_addc_u32 s13, s63, 0
	s_add_i32 s18, s18, 1
	s_mov_b64 s[14:15], -1
	s_nop 2
	global_load_dword v0, v173, s[12:13] sc1
	s_waitcnt vmcnt(0)
	v_cmp_ne_u32_e32 vcc, v0, v1
	s_orn2_b64 s[12:13], vcc, exec
	s_branch .LBB0_1008
